# v38 + half-step stagger of the two waves per SIMD in the diff loops with the s_setprio toggles replaced by s_nop
# baseline (speedup 1.0000x reference)
; template <int DQK>
; __device__ __forceinline__ void attn_pass4(LAS unsigned char* lds, const bf16* Qp, int qpitch, const bf16* Kp, int kpitch, const bf16* Vp, int vpitch, int q0, f32x16 (&o)[4], float (&rl)[16]) {
;     ...
;     const int NT = (q0 + 256) / 64;
;     const int qw0 = q0 + wid * 32;
;     const unsigned lds0 = (unsigned)(size_t)lds;
;     constexpr int KS = G::KP / 16, KD = DQK / 8, KJ = (KS + 7) / 8, VS = VP / 16, VD = 16, VJ = (VS + 7) / 8;
;     unsigned koff[KJ], voff[VJ];
; #pragma unroll
;     for (int j = 0; j < KJ; ++j) { const int sidx = (j * 8 + wid) * 64 + lane, row = (sidx / KS) & 63, c = sidx % KS; koff[j] = (unsigned)(row * kpitch + (c < KD ? c : KD - 1) * 8) * 2u; }
; #pragma unroll
;     for (int j = 0; j < VJ; ++j) { const int sidx = (j * 8 + wid) * 64 + lane, row = (sidx / VS) & 63, c = sidx % VS; voff[j] = (unsigned)(row * vpitch + (c < VD ? c : VD - 1) * 8) * 2u; }
;     ...
; #pragma unroll
;     for (int db = 0; db < 4; ++db)
; #pragma unroll
;         for (int r = 0; r < 16; ++r) o[db][r] = 0.f;
;     float mhat = 0.f, l = 0.f;
;     f32x16 negm;
; #pragma unroll
;     for (int r = 0; r < 16; ++r) negm[r] = 0.f;
;     u32x4 pw[4];
;     ...
;     if (!shifted) {
;         for (int t = 0; t < NT; ++t) {
;             const int vnext = ATT_VNEXT(vcur);
;             if (t + 1 < NT) ATT_DMA(t + 1, (t + 1) & 1, vnext);
.LBB0_619:
	s_andn2_b32 s5, s5, 63
	s_lshl_b32 s5, s5, 2
	s_add_i32 s8, s30, 0x100
	s_add_i32 s81, s5, 0
	s_waitcnt vmcnt(0) lgkmcnt(0)
	s_barrier
	v_and_b32_e32 v167, 63, v32
	s_add_i32 s81, s81, 0x13800
	s_lshr_b32 s31, s8, 6
	v_mul_u32_u24_e32 v35, 0x90, v34
	v_lshlrev_b32_e32 v36, 1, v32
	v_lshlrev_b32_e32 v37, 3, v32
	s_cmp_lt_i32 s3, 8
	s_mov_b64 s[70:71], -1
	v_cmp_gt_u32_e64 s[8:9], 32, v167
	v_add3_u32 v188, 0, v35, v168
	v_lshlrev_b32_e32 v190, 2, v180
	v_lshl_add_u32 v169, v34, 2, s81
	v_lshrrev_b32_e32 v192, 2, v32
	v_and_b32_e32 v184, 32, v36
	v_and_b32_e32 v186, 24, v37
	s_cbranch_scc0 .LBB0_642
	v_and_or_b32 v32, v192, 3, v190
	v_mad_u32_u24 v32, v32, s82, 0
	v_mov_b32_e32 v46, v33
	v_mov_b32_e32 v47, v33
	v_add3_u32 v194, v32, v184, v186
	v_mov_b32_e32 v32, v33
	v_mov_b32_e32 v34, v33
	v_mov_b32_e32 v35, v33
	v_mov_b32_e32 v36, v33
	v_mov_b32_e32 v37, v33
	v_mov_b32_e32 v38, v33
	v_mov_b32_e32 v39, v33
	v_mov_b32_e32 v40, v33
	v_mov_b32_e32 v41, v33
	v_mov_b32_e32 v42, v33
	v_mov_b32_e32 v43, v33
	v_mov_b32_e32 v44, v33
	v_mov_b32_e32 v45, v33
	v_mov_b64_e32 v[96:97], v[46:47]
	v_mov_b64_e32 v[80:81], v[46:47]
	v_mov_b64_e32 v[64:65], v[46:47]
	s_lshl_b32 s5, s3, 10
	v_mov_b32_e32 v196, 0
	v_mov_b64_e32 v[94:95], v[44:45]
	v_mov_b64_e32 v[92:93], v[42:43]
	v_mov_b64_e32 v[90:91], v[40:41]
	v_mov_b64_e32 v[88:89], v[38:39]
	v_mov_b64_e32 v[86:87], v[36:37]
	v_mov_b64_e32 v[84:85], v[34:35]
	v_mov_b64_e32 v[82:83], v[32:33]
	v_mov_b64_e32 v[78:79], v[44:45]
	v_mov_b64_e32 v[76:77], v[42:43]
	v_mov_b64_e32 v[74:75], v[40:41]
	v_mov_b64_e32 v[72:73], v[38:39]
	v_mov_b64_e32 v[70:71], v[36:37]
	v_mov_b64_e32 v[68:69], v[34:35]
	v_mov_b64_e32 v[66:67], v[32:33]
	v_mov_b64_e32 v[62:63], v[44:45]
	v_mov_b64_e32 v[60:61], v[42:43]
	v_mov_b64_e32 v[58:59], v[40:41]
	v_mov_b64_e32 v[56:57], v[38:39]
	v_mov_b64_e32 v[54:55], v[36:37]
	v_mov_b64_e32 v[52:53], v[34:35]
	v_mov_b64_e32 v[50:51], v[32:33]
	v_mov_b64_e32 v[48:49], v[46:47]
	s_add_i32 s26, s5, 0x4800
	s_or_b32 s27, s76, 31
	v_mov_b32_e32 v171, v33
	v_mov_b32_e32 v177, v33
	s_movk_i32 s80, 0x2000
	v_mov_b32_e32 v173, v33
	v_mov_b32_e32 v175, v33
	v_mov_b32_e32 v179, v33
	s_mov_b32 s24, 0
	s_mov_b32 s18, 63
	s_mov_b64 s[70:71], s[60:61]
	v_mov_b64_e32 v[46:47], v[44:45]
	v_mov_b64_e32 v[44:45], v[42:43]
	v_mov_b64_e32 v[42:43], v[40:41]
	v_mov_b64_e32 v[40:41], v[38:39]
	v_mov_b64_e32 v[38:39], v[36:37]
	v_mov_b64_e32 v[36:37], v[34:35]
	v_mov_b64_e32 v[34:35], v[32:33]
	v_mov_b32_e32 v182, 0
	s_mov_b32 s72, 0
	v_mov_b32_e32 v98, 0
	v_mov_b32_e32 v99, v196
	v_mov_b32_e32 v100, v196
	v_mov_b32_e32 v101, v196
	v_mov_b32_e32 v102, v196
	v_mov_b32_e32 v103, v196
	v_mov_b32_e32 v104, v196
	v_mov_b32_e32 v105, v196
	v_mov_b32_e32 v106, v196
	v_mov_b32_e32 v107, v196
	v_mov_b32_e32 v108, v196
	v_mov_b32_e32 v109, v196
	v_mov_b32_e32 v110, v196
	v_mov_b32_e32 v111, v196
	v_mov_b32_e32 v112, v196
	v_mov_b32_e32 v113, v196
	v_readfirstlane_b32 s32, v242
	s_cmpk_gt_u32 s32, 0xff
	s_cbranch_scc0 .Lstag_pre_0
	s_barrier
.Lstag_pre_0:
.LBB0_621:
	s_add_i32 s25, s24, 1
	s_cmp_lg_u32 s24, 2
	s_cselect_b32 s35, s25, 0
	s_add_i32 s25, s72, 1
	s_cmp_ge_u32 s25, s31
	s_cbranch_scc1 .LBB0_625
	s_bitcmp1_b32 s25, 0
	s_cselect_b32 s73, 0x2400, 0
	s_add_i32 m0, s73, s5
	s_andn2_b64 vcc, exec, s[10:11]
	global_load_lds_dwordx4 v170, s[70:71]
	s_cbranch_vccnz .LBB0_624
	s_add_i32 m0, s73, s80
	s_nop 0
	global_load_lds_dwordx4 v176, s[70:71]

.Lskip_v2_0:
.LBB0_625:
	s_sub_i32 s73, s18, 63
	s_cmp_gt_i32 s73, s27
	s_cbranch_scc1 .Lstag_skip_0
	s_bitcmp1_b32 s72, 0
	s_cselect_b32 s72, 0x2400, 0
	v_add_u32_e32 v32, s72, v188
	s_nop 0
	ds_read_b128 v[214:217], v32
	ds_read_b128 v[218:221], v32 offset:4608
	ds_read_b128 v[222:225], v32 offset:32
	ds_read_b128 v[226:229], v32 offset:4640
	ds_read_b128 v[230:233], v32 offset:64
	ds_read_b128 v[234:237], v32 offset:4672
	ds_read_b128 v[238:241], v32 offset:96
	ds_read_b128 v[244:247], v32 offset:4704
	s_waitcnt lgkmcnt(7)
	v_mfma_f32_32x32x16_bf16 v[114:129], v[214:217], v[146:149], v[98:113]
	s_waitcnt lgkmcnt(6)
	v_mfma_f32_32x32x16_bf16 v[130:145], v[218:221], v[146:149], v[98:113]
	s_waitcnt lgkmcnt(5)
	v_mfma_f32_32x32x16_bf16 v[114:129], v[222:225], v[150:153], v[114:129]
	s_waitcnt lgkmcnt(4)
	v_mfma_f32_32x32x16_bf16 v[130:145], v[226:229], v[150:153], v[130:145]
	s_waitcnt lgkmcnt(3)
	v_mfma_f32_32x32x16_bf16 v[114:129], v[230:233], v[154:157], v[114:129]
	s_waitcnt lgkmcnt(2)
	v_mfma_f32_32x32x16_bf16 v[130:145], v[234:237], v[154:157], v[130:145]
	s_waitcnt lgkmcnt(1)
	v_mfma_f32_32x32x16_bf16 v[114:129], v[238:241], v[158:161], v[114:129]
	s_waitcnt lgkmcnt(0)
	v_mfma_f32_32x32x16_bf16 v[130:145], v[244:247], v[158:161], v[130:145]
	s_nop 0
	s_cmp_le_i32 s18, s76
	s_cbranch_scc1 .LBB0_628
	v_add_u32_e32 v32, s18, v190
	v_sub_u32_e32 v32, v32, v166
	s_nop 1
	v_cmp_ge_i32_e32 vcc, 63, v32
	v_cmp_gt_i32_e64 s[72:73], 63, v32
	v_cmp_ge_i32_e64 s[74:75], 61, v32
	v_cndmask_b32_e32 v114, v208, v114, vcc
	v_cndmask_b32_e64 v115, v208, v115, s[72:73]
	v_cndmask_b32_e64 v116, v208, v116, s[74:75]
	v_cmp_ge_i32_e32 vcc, 60, v32
	v_cmp_ge_i32_e64 s[72:73], 55, v32
	v_cmp_ge_i32_e64 s[74:75], 54, v32
	v_cndmask_b32_e32 v117, v208, v117, vcc
	v_cndmask_b32_e64 v118, v208, v118, s[72:73]
	v_cndmask_b32_e64 v119, v208, v119, s[74:75]
	v_cmp_ge_i32_e32 vcc, 53, v32
	v_cmp_ge_i32_e64 s[72:73], 52, v32
	v_cmp_ge_i32_e64 s[74:75], 47, v32
	v_cndmask_b32_e32 v120, v208, v120, vcc
	v_cndmask_b32_e64 v121, v208, v121, s[72:73]
	v_cndmask_b32_e64 v122, v208, v122, s[74:75]
	v_cmp_ge_i32_e32 vcc, 46, v32
	v_cmp_ge_i32_e64 s[72:73], 45, v32
	v_cmp_ge_i32_e64 s[74:75], 44, v32
	v_cndmask_b32_e32 v123, v208, v123, vcc
	v_cndmask_b32_e64 v124, v208, v124, s[72:73]
	v_cndmask_b32_e64 v125, v208, v125, s[74:75]
	v_cmp_ge_i32_e32 vcc, 39, v32
	v_cmp_ge_i32_e64 s[72:73], 38, v32
	v_cmp_ge_i32_e64 s[74:75], 37, v32
	v_cndmask_b32_e32 v126, v208, v126, vcc
	v_cndmask_b32_e64 v127, v208, v127, s[72:73]
	v_cndmask_b32_e64 v128, v208, v128, s[74:75]
	v_cmp_ge_i32_e32 vcc, 36, v32
	v_cmp_ge_i32_e64 s[72:73], 31, v32
	v_cmp_ge_i32_e64 s[74:75], 30, v32
	v_cndmask_b32_e32 v129, v208, v129, vcc
	v_cndmask_b32_e64 v130, v208, v130, s[72:73]
	v_cndmask_b32_e64 v131, v208, v131, s[74:75]
	v_cmp_ge_i32_e32 vcc, 29, v32
	v_cmp_ge_i32_e64 s[72:73], 28, v32
	v_cmp_ge_i32_e64 s[74:75], 23, v32
	v_cndmask_b32_e32 v132, v208, v132, vcc
	v_cndmask_b32_e64 v133, v208, v133, s[72:73]
	v_cndmask_b32_e64 v134, v208, v134, s[74:75]
	v_cmp_ge_i32_e32 vcc, 22, v32
	v_cmp_ge_i32_e64 s[72:73], 21, v32
	v_cmp_ge_i32_e64 s[74:75], 20, v32
	v_cndmask_b32_e32 v135, v208, v135, vcc
	v_cndmask_b32_e64 v136, v208, v136, s[72:73]
	v_cndmask_b32_e64 v137, v208, v137, s[74:75]
	v_cmp_ge_i32_e32 vcc, 15, v32
	v_cmp_ge_i32_e64 s[72:73], 14, v32
	v_cmp_ge_i32_e64 s[74:75], 13, v32
	v_cndmask_b32_e32 v138, v208, v138, vcc
	v_cndmask_b32_e64 v139, v208, v139, s[72:73]
	v_cndmask_b32_e64 v140, v208, v140, s[74:75]
	v_cmp_ge_i32_e32 vcc, 12, v32
	v_cmp_ge_i32_e64 s[72:73], 7, v32
	v_cmp_ge_i32_e64 s[74:75], 6, v32
	v_cndmask_b32_e32 v141, v208, v141, vcc
	v_cndmask_b32_e64 v142, v208, v142, s[72:73]
	v_cndmask_b32_e64 v143, v208, v143, s[74:75]
	v_cmp_ge_i32_e32 vcc, 5, v32
	v_cmp_ge_i32_e64 s[72:73], 4, v32
	s_nop 0
	v_cndmask_b32_e32 v144, v208, v144, vcc
	v_cndmask_b32_e64 v145, v208, v145, s[72:73]

.LBB0_637:
	s_waitcnt vmcnt(0)
	s_barrier
	s_mulk_i32 s24, 0x5000
	v_add_u32_e32 v32, s24, v194
	s_nop 0
	ds_read_b64_tr_b16 v[214:215], v32 offset:18432
	ds_read_b64_tr_b16 v[216:217], v32 offset:20992
	ds_read_b64_tr_b16 v[218:219], v32 offset:18496
	ds_read_b64_tr_b16 v[220:221], v32 offset:21056
	ds_read_b64_tr_b16 v[222:223], v32 offset:18560
	ds_read_b64_tr_b16 v[224:225], v32 offset:21120
	ds_read_b64_tr_b16 v[226:227], v32 offset:18624
	ds_read_b64_tr_b16 v[228:229], v32 offset:21184
	ds_read_b64_tr_b16 v[230:231], v32 offset:23552
	ds_read_b64_tr_b16 v[232:233], v32 offset:26112
	v_exp_f32_e32 v114, v114
	v_exp_f32_e32 v115, v115
	v_exp_f32_e32 v116, v116
	v_exp_f32_e32 v117, v117
	v_exp_f32_e32 v118, v118
	v_cvt_pk_bf16_f32 v234, v114, v115
	v_exp_f32_e32 v119, v119
	v_cvt_pk_bf16_f32 v235, v116, v117
	v_exp_f32_e32 v120, v120
	v_exp_f32_e32 v121, v121
	v_cvt_pk_bf16_f32 v236, v118, v119
	s_nop 0
	v_cvt_pk_bf16_f32 v237, v120, v121
	s_nop 1
	s_waitcnt lgkmcnt(8)
	v_mfma_f32_32x32x16_bf16 v[82:97], v[234:237], v[214:217], v[82:97]
	ds_read_b64_tr_b16 v[214:215], v32 offset:23616
	ds_read_b64_tr_b16 v[216:217], v32 offset:26176
	v_exp_f32_e32 v122, v122
	v_exp_f32_e32 v123, v123
	v_exp_f32_e32 v124, v124
	s_waitcnt lgkmcnt(8)
	v_mfma_f32_32x32x16_bf16 v[66:81], v[234:237], v[218:221], v[66:81]
	ds_read_b64_tr_b16 v[218:219], v32 offset:23680
	ds_read_b64_tr_b16 v[220:221], v32 offset:26240
	v_exp_f32_e32 v125, v125
	v_exp_f32_e32 v126, v126
	v_exp_f32_e32 v127, v127
	v_cvt_pk_bf16_f32 v238, v122, v123
	v_add_f32_e32 v252, v114, v115
	s_waitcnt lgkmcnt(8)
	v_mfma_f32_32x32x16_bf16 v[50:65], v[234:237], v[222:225], v[50:65]
	ds_read_b64_tr_b16 v[222:223], v32 offset:23744
	ds_read_b64_tr_b16 v[224:225], v32 offset:26304
	v_exp_f32_e32 v128, v128
	v_exp_f32_e32 v129, v129
	v_cvt_pk_bf16_f32 v239, v124, v125
	v_add_f32_e32 v253, v116, v117
	s_waitcnt lgkmcnt(8)
	v_mfma_f32_32x32x16_bf16 v[34:49], v[234:237], v[226:229], v[34:49]
	ds_read_b64_tr_b16 v[226:227], v32 offset:28672
	ds_read_b64_tr_b16 v[228:229], v32 offset:31232
	v_cvt_pk_bf16_f32 v240, v126, v127
	v_cvt_pk_bf16_f32 v241, v128, v129
	v_add_f32_e32 v254, v118, v119
	v_add_f32_e32 v213, v120, v121
	s_waitcnt lgkmcnt(8)
	v_mfma_f32_32x32x16_bf16 v[82:97], v[238:241], v[230:233], v[82:97]
	ds_read_b64_tr_b16 v[230:231], v32 offset:28736
	ds_read_b64_tr_b16 v[232:233], v32 offset:31296
	v_exp_f32_e32 v130, v130
	v_exp_f32_e32 v131, v131
	v_exp_f32_e32 v132, v132
	v_add_f32_e32 v252, v252, v122
	s_waitcnt lgkmcnt(8)
	v_mfma_f32_32x32x16_bf16 v[66:81], v[238:241], v[214:217], v[66:81]
	ds_read_b64_tr_b16 v[214:215], v32 offset:28800
	ds_read_b64_tr_b16 v[216:217], v32 offset:31360
	v_exp_f32_e32 v133, v133
	v_exp_f32_e32 v134, v134
	v_exp_f32_e32 v135, v135
	v_cvt_pk_bf16_f32 v244, v130, v131
	v_add_f32_e32 v253, v253, v123
	s_waitcnt lgkmcnt(8)
	v_mfma_f32_32x32x16_bf16 v[50:65], v[238:241], v[218:221], v[50:65]
	ds_read_b64_tr_b16 v[218:219], v32 offset:28864
	ds_read_b64_tr_b16 v[220:221], v32 offset:31424
	v_exp_f32_e32 v136, v136
	v_exp_f32_e32 v137, v137
	v_cvt_pk_bf16_f32 v245, v132, v133
	v_add_f32_e32 v254, v254, v124
	v_add_f32_e32 v213, v213, v125
	s_waitcnt lgkmcnt(8)
	v_mfma_f32_32x32x16_bf16 v[34:49], v[238:241], v[222:225], v[34:49]
	ds_read_b64_tr_b16 v[222:223], v32 offset:33792
	ds_read_b64_tr_b16 v[224:225], v32 offset:36352
	v_cvt_pk_bf16_f32 v246, v134, v135
	v_add_f32_e32 v252, v252, v126
	v_cvt_pk_bf16_f32 v247, v136, v137
	v_add_f32_e32 v253, v253, v127
	v_add_f32_e32 v254, v254, v128
	v_add_f32_e32 v213, v213, v129
	s_waitcnt lgkmcnt(8)
	v_mfma_f32_32x32x16_bf16 v[82:97], v[244:247], v[226:229], v[82:97]
	ds_read_b64_tr_b16 v[226:227], v32 offset:33856
	ds_read_b64_tr_b16 v[228:229], v32 offset:36416
	v_exp_f32_e32 v138, v138
	v_exp_f32_e32 v139, v139
	v_exp_f32_e32 v140, v140
	v_add_f32_e32 v252, v252, v130
	s_waitcnt lgkmcnt(8)
	v_mfma_f32_32x32x16_bf16 v[66:81], v[244:247], v[230:233], v[66:81]
	ds_read_b64_tr_b16 v[230:231], v32 offset:33920
	ds_read_b64_tr_b16 v[232:233], v32 offset:36480
	v_exp_f32_e32 v141, v141
	v_exp_f32_e32 v142, v142
	v_exp_f32_e32 v143, v143
	v_cvt_pk_bf16_f32 v248, v138, v139
	v_add_f32_e32 v253, v253, v131
	s_waitcnt lgkmcnt(8)
	v_mfma_f32_32x32x16_bf16 v[50:65], v[244:247], v[214:217], v[50:65]
	ds_read_b64_tr_b16 v[214:215], v32 offset:33984
	ds_read_b64_tr_b16 v[216:217], v32 offset:36544
	v_exp_f32_e32 v144, v144
	v_exp_f32_e32 v145, v145
	v_cvt_pk_bf16_f32 v249, v140, v141
	v_add_f32_e32 v254, v254, v132
	v_add_f32_e32 v213, v213, v133
	s_waitcnt lgkmcnt(8)
	v_mfma_f32_32x32x16_bf16 v[34:49], v[244:247], v[218:221], v[34:49]
	v_cvt_pk_bf16_f32 v250, v142, v143
	v_add_f32_e32 v252, v252, v134
	v_cvt_pk_bf16_f32 v251, v144, v145
	v_add_f32_e32 v253, v253, v135
	v_add_f32_e32 v254, v254, v136
	v_add_f32_e32 v213, v213, v137
	s_waitcnt lgkmcnt(6)
	v_mfma_f32_32x32x16_bf16 v[82:97], v[248:251], v[222:225], v[82:97]
	v_add_f32_e32 v252, v252, v138
	v_add_f32_e32 v253, v253, v139
	v_add_f32_e32 v254, v254, v140
	s_waitcnt lgkmcnt(4)
	v_mfma_f32_32x32x16_bf16 v[66:81], v[248:251], v[226:229], v[66:81]
	v_add_f32_e32 v213, v213, v141
	v_add_f32_e32 v252, v252, v142
	v_add_f32_e32 v253, v253, v143
	s_waitcnt lgkmcnt(2)
	v_mfma_f32_32x32x16_bf16 v[50:65], v[248:251], v[230:233], v[50:65]
	v_add_f32_e32 v254, v254, v144
	v_add_f32_e32 v213, v213, v145
	v_add_f32_e32 v252, v252, v253
	v_add_f32_e32 v254, v254, v213
	s_waitcnt lgkmcnt(0)
	v_mfma_f32_32x32x16_bf16 v[34:49], v[248:251], v[214:217], v[34:49]
	v_add_f32_e32 v252, v252, v254
	v_add_f32_e32 v182, v182, v252
	s_nop 0

; #define ATT_BAR() asm volatile("s_waitcnt lgkmcnt(0)\n\ts_barrier" ::: "memory")
; #define ATT_BAR() asm volatile("s_waitcnt vmcnt(0) lgkmcnt(0)\n\ts_barrier" ::: "memory")
; template <int DQK>
; __device__ __forceinline__ void attn_pass4(LAS unsigned char* lds, const bf16* Qp, int qpitch, const bf16* Kp, int kpitch, const bf16* Vp, int vpitch, int q0, f32x16 (&o)[4], float (&rl)[16]) {
;     ...
;     if (!shifted) {
;         for (int t = 0; t < NT; ++t) {
;             const int vnext = ATT_VNEXT(vcur);
;             if (t + 1 < NT) ATT_DMA(t + 1, (t + 1) & 1, vnext);
;             if (ATT_VIS(t)) { ATT_A(t); ATT_B(vcur); }
;             vcur = vnext;
;             ATT_BAR();
;         }
;     } else {
;         int vprev = 2;
;         for (int t = 0; t < NT; ++t) {
;             const int vnext = ATT_VNEXT(vcur);
;             if (t + 1 < NT) ATT_DMA(t + 1, (t + 1) & 1, vnext);
;             if (t > 0 && ATT_VIS(t - 1)) ATT_B(vprev);
;             if (ATT_VIS(t)) ATT_A(t);
;             vprev = vcur; vcur = vnext;
;             ATT_BAR();
;         }
;         if (ATT_VIS(NT - 1)) ATT_B(vprev);
;     }
.Lstag_skip_0:
	s_waitcnt vmcnt(0)
	s_barrier
	s_branch .LBB0_638
.LBB0_641:
	v_readfirstlane_b32 s32, v242
	s_cmpk_gt_u32 s32, 0xff
	s_cbranch_scc1 .Lstag_post_0
	s_barrier

; template <int DQK>
; __device__ __forceinline__ void attn_pass4(LAS unsigned char* lds, const bf16* Qp, int qpitch, const bf16* Kp, int kpitch, const bf16* Vp, int vpitch, int q0, f32x16 (&o)[4], float (&rl)[16]) {
;     ...
;     const int NT = (q0 + 256) / 64;
;     const int qw0 = q0 + wid * 32;
;     const unsigned lds0 = (unsigned)(size_t)lds;
;     constexpr int KS = G::KP / 16, KD = DQK / 8, KJ = (KS + 7) / 8, VS = VP / 16, VD = 16, VJ = (VS + 7) / 8;
;     unsigned koff[KJ], voff[VJ];
; #pragma unroll
;     for (int j = 0; j < KJ; ++j) { const int sidx = (j * 8 + wid) * 64 + lane, row = (sidx / KS) & 63, c = sidx % KS; koff[j] = (unsigned)(row * kpitch + (c < KD ? c : KD - 1) * 8) * 2u; }
; #pragma unroll
;     for (int j = 0; j < VJ; ++j) { const int sidx = (j * 8 + wid) * 64 + lane, row = (sidx / VS) & 63, c = sidx % VS; voff[j] = (unsigned)(row * vpitch + (c < VD ? c : VD - 1) * 8) * 2u; }
;     ...
; #pragma unroll
;     for (int db = 0; db < 4; ++db)
; #pragma unroll
;         for (int r = 0; r < 16; ++r) o[db][r] = 0.f;
;     float mhat = 0.f, l = 0.f;
;     f32x16 negm;
; #pragma unroll
;     for (int r = 0; r < 16; ++r) negm[r] = 0.f;
;     u32x4 pw[4];
;     ...
;     if (!shifted) {
;         for (int t = 0; t < NT; ++t) {
;             const int vnext = ATT_VNEXT(vcur);
;             if (t + 1 < NT) ATT_DMA(t + 1, (t + 1) & 1, vnext);
.LBB0_819:
	s_andn2_b32 s3, s3, 63
	s_lshl_b32 s3, s3, 2
	s_add_i32 s81, s3, 0
	s_waitcnt vmcnt(0) lgkmcnt(0)
	s_barrier
	v_and_b32_e32 v167, 63, v32
	s_add_i32 s81, s81, 0x13800
	v_mul_u32_u24_e32 v35, 0x90, v34
	v_lshlrev_b32_e32 v36, 1, v32
	v_lshlrev_b32_e32 v37, 3, v32
	s_cmp_lt_i32 s80, 8
	s_mov_b64 s[70:71], -1
	v_cmp_gt_u32_e64 s[8:9], 32, v167
	v_add3_u32 v188, 0, v35, v168
	v_lshlrev_b32_e32 v190, 2, v180
	v_lshl_add_u32 v169, v34, 2, s81
	v_lshrrev_b32_e32 v192, 2, v32
	v_and_b32_e32 v184, 32, v36
	v_and_b32_e32 v186, 24, v37
	s_cbranch_scc0 .LBB0_842
	v_and_or_b32 v32, v192, 3, v190
	v_mad_u32_u24 v32, v32, s82, 0
	v_mov_b32_e32 v46, v33
	v_mov_b32_e32 v47, v33
	v_add3_u32 v194, v32, v184, v186
	v_mov_b32_e32 v32, v33
	v_mov_b32_e32 v34, v33
	v_mov_b32_e32 v35, v33
	v_mov_b32_e32 v36, v33
	v_mov_b32_e32 v37, v33
	v_mov_b32_e32 v38, v33
	v_mov_b32_e32 v39, v33
	v_mov_b32_e32 v40, v33
	v_mov_b32_e32 v41, v33
	v_mov_b32_e32 v42, v33
	v_mov_b32_e32 v43, v33
	v_mov_b32_e32 v44, v33
	v_mov_b32_e32 v45, v33
	v_mov_b64_e32 v[96:97], v[46:47]
	v_mov_b64_e32 v[80:81], v[46:47]
	v_mov_b64_e32 v[64:65], v[46:47]
	s_lshl_b32 s3, s80, 10
	v_mov_b32_e32 v196, 0
	v_mov_b64_e32 v[94:95], v[44:45]
	v_mov_b64_e32 v[92:93], v[42:43]
	v_mov_b64_e32 v[90:91], v[40:41]
	v_mov_b64_e32 v[88:89], v[38:39]
	v_mov_b64_e32 v[86:87], v[36:37]
	v_mov_b64_e32 v[84:85], v[34:35]
	v_mov_b64_e32 v[82:83], v[32:33]
	v_mov_b64_e32 v[78:79], v[44:45]
	v_mov_b64_e32 v[76:77], v[42:43]
	v_mov_b64_e32 v[74:75], v[40:41]
	v_mov_b64_e32 v[72:73], v[38:39]
	v_mov_b64_e32 v[70:71], v[36:37]
	v_mov_b64_e32 v[68:69], v[34:35]
	v_mov_b64_e32 v[66:67], v[32:33]
	v_mov_b64_e32 v[62:63], v[44:45]
	v_mov_b64_e32 v[60:61], v[42:43]
	v_mov_b64_e32 v[58:59], v[40:41]
	v_mov_b64_e32 v[56:57], v[38:39]
	v_mov_b64_e32 v[54:55], v[36:37]
	v_mov_b64_e32 v[52:53], v[34:35]
	v_mov_b64_e32 v[50:51], v[32:33]
	v_mov_b64_e32 v[48:49], v[46:47]
	s_add_i32 s5, s3, 0x4800
	s_or_b32 s26, s76, 31
	v_mov_b32_e32 v171, v33
	v_mov_b32_e32 v177, v33
	s_movk_i32 s27, 0x2000
	v_mov_b32_e32 v173, v33
	v_mov_b32_e32 v175, v33
	v_mov_b32_e32 v179, v33
	s_mov_b32 s35, 0
	s_mov_b32 s18, 63
	s_mov_b64 s[70:71], s[62:63]
	v_mov_b64_e32 v[46:47], v[44:45]
	v_mov_b64_e32 v[44:45], v[42:43]
	v_mov_b64_e32 v[42:43], v[40:41]
	v_mov_b64_e32 v[40:41], v[38:39]
	v_mov_b64_e32 v[38:39], v[36:37]
	v_mov_b64_e32 v[36:37], v[34:35]
	v_mov_b64_e32 v[34:35], v[32:33]
	v_mov_b32_e32 v182, 0
	s_mov_b32 s72, 0
	v_mov_b32_e32 v98, 0
	v_mov_b32_e32 v99, v196
	v_mov_b32_e32 v100, v196
	v_mov_b32_e32 v101, v196
	v_mov_b32_e32 v102, v196
	v_mov_b32_e32 v103, v196
	v_mov_b32_e32 v104, v196
	v_mov_b32_e32 v105, v196
	v_mov_b32_e32 v106, v196
	v_mov_b32_e32 v107, v196
	v_mov_b32_e32 v108, v196
	v_mov_b32_e32 v109, v196
	v_mov_b32_e32 v110, v196
	v_mov_b32_e32 v111, v196
	v_mov_b32_e32 v112, v196
	v_mov_b32_e32 v113, v196
	v_readfirstlane_b32 s32, v242
	s_cmpk_gt_u32 s32, 0xff
	s_cbranch_scc0 .Lstag_pre_1
	s_barrier
.Lstag_pre_1:
.LBB0_821:
	s_add_i32 s24, s35, 1
	s_cmp_lg_u32 s35, 2
	s_cselect_b32 s24, s24, 0
	s_add_i32 s25, s72, 1
	s_cmp_ge_u32 s25, s31
	s_cbranch_scc1 .LBB0_825
	s_bitcmp1_b32 s25, 0
	s_cselect_b32 s73, 0x2400, 0
	s_add_i32 m0, s73, s3
	s_andn2_b64 vcc, exec, s[10:11]
	global_load_lds_dwordx4 v170, s[70:71]
	s_cbranch_vccnz .LBB0_824
	s_add_i32 m0, s73, s27
	s_nop 0
	global_load_lds_dwordx4 v176, s[70:71]

.Lskip_v2_1:
.LBB0_825:
	s_sub_i32 s73, s18, 63
	s_cmp_gt_i32 s73, s26
	s_cbranch_scc1 .Lstag_skip_1
	s_bitcmp1_b32 s72, 0
	s_cselect_b32 s72, 0x2400, 0
	v_add_u32_e32 v32, s72, v188
	s_nop 0
	ds_read_b128 v[214:217], v32
	ds_read_b128 v[218:221], v32 offset:4608
	ds_read_b128 v[222:225], v32 offset:32
	ds_read_b128 v[226:229], v32 offset:4640
	ds_read_b128 v[230:233], v32 offset:64
	ds_read_b128 v[234:237], v32 offset:4672
	ds_read_b128 v[238:241], v32 offset:96
	ds_read_b128 v[244:247], v32 offset:4704
	s_waitcnt lgkmcnt(7)
	v_mfma_f32_32x32x16_bf16 v[114:129], v[214:217], v[146:149], v[98:113]
	s_waitcnt lgkmcnt(6)
	v_mfma_f32_32x32x16_bf16 v[130:145], v[218:221], v[146:149], v[98:113]
	s_waitcnt lgkmcnt(5)
	v_mfma_f32_32x32x16_bf16 v[114:129], v[222:225], v[150:153], v[114:129]
	s_waitcnt lgkmcnt(4)
	v_mfma_f32_32x32x16_bf16 v[130:145], v[226:229], v[150:153], v[130:145]
	s_waitcnt lgkmcnt(3)
	v_mfma_f32_32x32x16_bf16 v[114:129], v[230:233], v[154:157], v[114:129]
	s_waitcnt lgkmcnt(2)
	v_mfma_f32_32x32x16_bf16 v[130:145], v[234:237], v[154:157], v[130:145]
	s_waitcnt lgkmcnt(1)
	v_mfma_f32_32x32x16_bf16 v[114:129], v[238:241], v[158:161], v[114:129]
	s_waitcnt lgkmcnt(0)
	v_mfma_f32_32x32x16_bf16 v[130:145], v[244:247], v[158:161], v[130:145]
	s_nop 0
	s_cmp_le_i32 s18, s76
	s_cbranch_scc1 .LBB0_828
	v_add_u32_e32 v32, s18, v190
	v_sub_u32_e32 v32, v32, v166
	s_nop 1
	v_cmp_ge_i32_e32 vcc, 63, v32
	v_cmp_gt_i32_e64 s[72:73], 63, v32
	v_cmp_ge_i32_e64 s[74:75], 61, v32
	v_cndmask_b32_e32 v114, v208, v114, vcc
	v_cndmask_b32_e64 v115, v208, v115, s[72:73]
	v_cndmask_b32_e64 v116, v208, v116, s[74:75]
	v_cmp_ge_i32_e32 vcc, 60, v32
	v_cmp_ge_i32_e64 s[72:73], 55, v32
	v_cmp_ge_i32_e64 s[74:75], 54, v32
	v_cndmask_b32_e32 v117, v208, v117, vcc
	v_cndmask_b32_e64 v118, v208, v118, s[72:73]
	v_cndmask_b32_e64 v119, v208, v119, s[74:75]
	v_cmp_ge_i32_e32 vcc, 53, v32
	v_cmp_ge_i32_e64 s[72:73], 52, v32
	v_cmp_ge_i32_e64 s[74:75], 47, v32
	v_cndmask_b32_e32 v120, v208, v120, vcc
	v_cndmask_b32_e64 v121, v208, v121, s[72:73]
	v_cndmask_b32_e64 v122, v208, v122, s[74:75]
	v_cmp_ge_i32_e32 vcc, 46, v32
	v_cmp_ge_i32_e64 s[72:73], 45, v32
	v_cmp_ge_i32_e64 s[74:75], 44, v32
	v_cndmask_b32_e32 v123, v208, v123, vcc
	v_cndmask_b32_e64 v124, v208, v124, s[72:73]
	v_cndmask_b32_e64 v125, v208, v125, s[74:75]
	v_cmp_ge_i32_e32 vcc, 39, v32
	v_cmp_ge_i32_e64 s[72:73], 38, v32
	v_cmp_ge_i32_e64 s[74:75], 37, v32
	v_cndmask_b32_e32 v126, v208, v126, vcc
	v_cndmask_b32_e64 v127, v208, v127, s[72:73]
	v_cndmask_b32_e64 v128, v208, v128, s[74:75]
	v_cmp_ge_i32_e32 vcc, 36, v32
	v_cmp_ge_i32_e64 s[72:73], 31, v32
	v_cmp_ge_i32_e64 s[74:75], 30, v32
	v_cndmask_b32_e32 v129, v208, v129, vcc
	v_cndmask_b32_e64 v130, v208, v130, s[72:73]
	v_cndmask_b32_e64 v131, v208, v131, s[74:75]
	v_cmp_ge_i32_e32 vcc, 29, v32
	v_cmp_ge_i32_e64 s[72:73], 28, v32
	v_cmp_ge_i32_e64 s[74:75], 23, v32
	v_cndmask_b32_e32 v132, v208, v132, vcc
	v_cndmask_b32_e64 v133, v208, v133, s[72:73]
	v_cndmask_b32_e64 v134, v208, v134, s[74:75]
	v_cmp_ge_i32_e32 vcc, 22, v32
	v_cmp_ge_i32_e64 s[72:73], 21, v32
	v_cmp_ge_i32_e64 s[74:75], 20, v32
	v_cndmask_b32_e32 v135, v208, v135, vcc
	v_cndmask_b32_e64 v136, v208, v136, s[72:73]
	v_cndmask_b32_e64 v137, v208, v137, s[74:75]
	v_cmp_ge_i32_e32 vcc, 15, v32
	v_cmp_ge_i32_e64 s[72:73], 14, v32
	v_cmp_ge_i32_e64 s[74:75], 13, v32
	v_cndmask_b32_e32 v138, v208, v138, vcc
	v_cndmask_b32_e64 v139, v208, v139, s[72:73]
	v_cndmask_b32_e64 v140, v208, v140, s[74:75]
	v_cmp_ge_i32_e32 vcc, 12, v32
	v_cmp_ge_i32_e64 s[72:73], 7, v32
	v_cmp_ge_i32_e64 s[74:75], 6, v32
	v_cndmask_b32_e32 v141, v208, v141, vcc
	v_cndmask_b32_e64 v142, v208, v142, s[72:73]
	v_cndmask_b32_e64 v143, v208, v143, s[74:75]
	v_cmp_ge_i32_e32 vcc, 5, v32
	v_cmp_ge_i32_e64 s[72:73], 4, v32
	s_nop 0
	v_cndmask_b32_e32 v144, v208, v144, vcc
	v_cndmask_b32_e64 v145, v208, v145, s[72:73]

.LBB0_837:
	s_waitcnt vmcnt(0)
	s_barrier
	s_mulk_i32 s35, 0x5000
	v_add_u32_e32 v32, s35, v194
	s_nop 0
	ds_read_b64_tr_b16 v[214:215], v32 offset:18432
	ds_read_b64_tr_b16 v[216:217], v32 offset:20992
	ds_read_b64_tr_b16 v[218:219], v32 offset:18496
	ds_read_b64_tr_b16 v[220:221], v32 offset:21056
	ds_read_b64_tr_b16 v[222:223], v32 offset:18560
	ds_read_b64_tr_b16 v[224:225], v32 offset:21120
	ds_read_b64_tr_b16 v[226:227], v32 offset:18624
	ds_read_b64_tr_b16 v[228:229], v32 offset:21184
	ds_read_b64_tr_b16 v[230:231], v32 offset:23552
	ds_read_b64_tr_b16 v[232:233], v32 offset:26112
	v_exp_f32_e32 v114, v114
	v_exp_f32_e32 v115, v115
	v_exp_f32_e32 v116, v116
	v_exp_f32_e32 v117, v117
	v_exp_f32_e32 v118, v118
	v_cvt_pk_bf16_f32 v234, v114, v115
	v_exp_f32_e32 v119, v119
	v_cvt_pk_bf16_f32 v235, v116, v117
	v_exp_f32_e32 v120, v120
	v_exp_f32_e32 v121, v121
	v_cvt_pk_bf16_f32 v236, v118, v119
	s_nop 0
	v_cvt_pk_bf16_f32 v237, v120, v121
	s_nop 1
	s_waitcnt lgkmcnt(8)
	v_mfma_f32_32x32x16_bf16 v[82:97], v[234:237], v[214:217], v[82:97]
	ds_read_b64_tr_b16 v[214:215], v32 offset:23616
	ds_read_b64_tr_b16 v[216:217], v32 offset:26176
	v_exp_f32_e32 v122, v122
	v_exp_f32_e32 v123, v123
	v_exp_f32_e32 v124, v124
	s_waitcnt lgkmcnt(8)
	v_mfma_f32_32x32x16_bf16 v[66:81], v[234:237], v[218:221], v[66:81]
	ds_read_b64_tr_b16 v[218:219], v32 offset:23680
	ds_read_b64_tr_b16 v[220:221], v32 offset:26240
	v_exp_f32_e32 v125, v125
	v_exp_f32_e32 v126, v126
	v_exp_f32_e32 v127, v127
	v_cvt_pk_bf16_f32 v238, v122, v123
	v_add_f32_e32 v252, v114, v115
	s_waitcnt lgkmcnt(8)
	v_mfma_f32_32x32x16_bf16 v[50:65], v[234:237], v[222:225], v[50:65]
	ds_read_b64_tr_b16 v[222:223], v32 offset:23744
	ds_read_b64_tr_b16 v[224:225], v32 offset:26304
	v_exp_f32_e32 v128, v128
	v_exp_f32_e32 v129, v129
	v_cvt_pk_bf16_f32 v239, v124, v125
	v_add_f32_e32 v253, v116, v117
	s_waitcnt lgkmcnt(8)
	v_mfma_f32_32x32x16_bf16 v[34:49], v[234:237], v[226:229], v[34:49]
	ds_read_b64_tr_b16 v[226:227], v32 offset:28672
	ds_read_b64_tr_b16 v[228:229], v32 offset:31232
	v_cvt_pk_bf16_f32 v240, v126, v127
	v_cvt_pk_bf16_f32 v241, v128, v129
	v_add_f32_e32 v254, v118, v119
	v_add_f32_e32 v213, v120, v121
	s_waitcnt lgkmcnt(8)
	v_mfma_f32_32x32x16_bf16 v[82:97], v[238:241], v[230:233], v[82:97]
	ds_read_b64_tr_b16 v[230:231], v32 offset:28736
	ds_read_b64_tr_b16 v[232:233], v32 offset:31296
	v_exp_f32_e32 v130, v130
	v_exp_f32_e32 v131, v131
	v_exp_f32_e32 v132, v132
	v_add_f32_e32 v252, v252, v122
	s_waitcnt lgkmcnt(8)
	v_mfma_f32_32x32x16_bf16 v[66:81], v[238:241], v[214:217], v[66:81]
	ds_read_b64_tr_b16 v[214:215], v32 offset:28800
	ds_read_b64_tr_b16 v[216:217], v32 offset:31360
	v_exp_f32_e32 v133, v133
	v_exp_f32_e32 v134, v134
	v_exp_f32_e32 v135, v135
	v_cvt_pk_bf16_f32 v244, v130, v131
	v_add_f32_e32 v253, v253, v123
	s_waitcnt lgkmcnt(8)
	v_mfma_f32_32x32x16_bf16 v[50:65], v[238:241], v[218:221], v[50:65]
	ds_read_b64_tr_b16 v[218:219], v32 offset:28864
	ds_read_b64_tr_b16 v[220:221], v32 offset:31424
	v_exp_f32_e32 v136, v136
	v_exp_f32_e32 v137, v137
	v_cvt_pk_bf16_f32 v245, v132, v133
	v_add_f32_e32 v254, v254, v124
	v_add_f32_e32 v213, v213, v125
	s_waitcnt lgkmcnt(8)
	v_mfma_f32_32x32x16_bf16 v[34:49], v[238:241], v[222:225], v[34:49]
	ds_read_b64_tr_b16 v[222:223], v32 offset:33792
	ds_read_b64_tr_b16 v[224:225], v32 offset:36352
	v_cvt_pk_bf16_f32 v246, v134, v135
	v_add_f32_e32 v252, v252, v126
	v_cvt_pk_bf16_f32 v247, v136, v137
	v_add_f32_e32 v253, v253, v127
	v_add_f32_e32 v254, v254, v128
	v_add_f32_e32 v213, v213, v129
	s_waitcnt lgkmcnt(8)
	v_mfma_f32_32x32x16_bf16 v[82:97], v[244:247], v[226:229], v[82:97]
	ds_read_b64_tr_b16 v[226:227], v32 offset:33856
	ds_read_b64_tr_b16 v[228:229], v32 offset:36416
	v_exp_f32_e32 v138, v138
	v_exp_f32_e32 v139, v139
	v_exp_f32_e32 v140, v140
	v_add_f32_e32 v252, v252, v130
	s_waitcnt lgkmcnt(8)
	v_mfma_f32_32x32x16_bf16 v[66:81], v[244:247], v[230:233], v[66:81]
	ds_read_b64_tr_b16 v[230:231], v32 offset:33920
	ds_read_b64_tr_b16 v[232:233], v32 offset:36480
	v_exp_f32_e32 v141, v141
	v_exp_f32_e32 v142, v142
	v_exp_f32_e32 v143, v143
	v_cvt_pk_bf16_f32 v248, v138, v139
	v_add_f32_e32 v253, v253, v131
	s_waitcnt lgkmcnt(8)
	v_mfma_f32_32x32x16_bf16 v[50:65], v[244:247], v[214:217], v[50:65]
	ds_read_b64_tr_b16 v[214:215], v32 offset:33984
	ds_read_b64_tr_b16 v[216:217], v32 offset:36544
	v_exp_f32_e32 v144, v144
	v_exp_f32_e32 v145, v145
	v_cvt_pk_bf16_f32 v249, v140, v141
	v_add_f32_e32 v254, v254, v132
	v_add_f32_e32 v213, v213, v133
	s_waitcnt lgkmcnt(8)
	v_mfma_f32_32x32x16_bf16 v[34:49], v[244:247], v[218:221], v[34:49]
	v_cvt_pk_bf16_f32 v250, v142, v143
	v_add_f32_e32 v252, v252, v134
	v_cvt_pk_bf16_f32 v251, v144, v145
	v_add_f32_e32 v253, v253, v135
	v_add_f32_e32 v254, v254, v136
	v_add_f32_e32 v213, v213, v137
	s_waitcnt lgkmcnt(6)
	v_mfma_f32_32x32x16_bf16 v[82:97], v[248:251], v[222:225], v[82:97]
	v_add_f32_e32 v252, v252, v138
	v_add_f32_e32 v253, v253, v139
	v_add_f32_e32 v254, v254, v140
	s_waitcnt lgkmcnt(4)
	v_mfma_f32_32x32x16_bf16 v[66:81], v[248:251], v[226:229], v[66:81]
	v_add_f32_e32 v213, v213, v141
	v_add_f32_e32 v252, v252, v142
	v_add_f32_e32 v253, v253, v143
	s_waitcnt lgkmcnt(2)
	v_mfma_f32_32x32x16_bf16 v[50:65], v[248:251], v[230:233], v[50:65]
	v_add_f32_e32 v254, v254, v144
	v_add_f32_e32 v213, v213, v145
	v_add_f32_e32 v252, v252, v253
	v_add_f32_e32 v254, v254, v213
	s_waitcnt lgkmcnt(0)
	v_mfma_f32_32x32x16_bf16 v[34:49], v[248:251], v[214:217], v[34:49]
	v_add_f32_e32 v252, v252, v254
	v_add_f32_e32 v182, v182, v252
	s_nop 0
